# differential-attention K tile: 16-B chunk XOR swizzle by row&15 (conflict-free ds_read_b128) instead of row&7
# speedup vs baseline: 1.0066x; 1.0066x over previous
.LBB0_303:
	v_mbcnt_lo_u32_b32 v195, -1, 0
	v_mbcnt_hi_u32_b32 v195, -1, v195
	s_movk_i32 s6, 0x400
	v_bfe_u32 v3, v195, 4, 2
	v_and_b32_e32 v5, 15, v195
	s_waitcnt lgkmcnt(1)
	v_or_b32_e32 v4, s85, v3
	v_bitop3_b32 v6, v3, v195, 15 bitop3:0x78
	v_bitop3_b32 v3, v3, v5, 4 bitop3:0x36
	v_lshlrev_b32_e32 v4, 8, v4
	v_lshlrev_b32_e32 v3, 4, v3
	v_lshl_or_b32 v197, v6, 4, v4
	v_or3_b32 v198, v3, v4, s6
	s_and_b32 s98, s85, 8
	s_lshl_b32 s98, s98, 4
	v_xor_b32_e32 v197, s98, v197
	v_xor_b32_e32 v198, s98, v198
	v_bfe_u32 v3, v195, 2, 3
	v_lshrrev_b32_e32 v4, 2, v195
	v_and_b32_e32 v196, 63, v195
	v_bitop3_b32 v3, v3, 51, s85 bitop3:0xc8
	v_and_b32_e32 v4, 4, v4
	s_waitcnt lgkmcnt(0)
	v_lshlrev_b32_e32 v1, 3, v196
	v_lshl_or_b32 v3, s96, 1, v3
	v_or_b32_e32 v3, v4, v3
	v_and_b32_e32 v2, 24, v1
	v_lshlrev_b32_e32 v3, 7, v3
	v_and_b32_e32 v4, 32, v195
	v_or3_b32 v3, v3, v4, v2
	v_lshlrev_b32_e32 v199, 1, v3
	s_andn2_b64 vcc, exec, s[56:57]
	v_or_b32_e32 v200, 0x80, v199
	s_cbranch_vccnz .LBB0_305
	s_mov_b32 s6, m0
	s_mov_b32 m0, s42
	s_nop 0
	global_load_lds_dwordx4 v197, s[4:5]
	s_mov_b32 m0, s6
	s_add_u32 s44, s4, 0x4000
	s_mov_b32 s6, m0
	s_mov_b32 m0, s43
	s_nop 0
	global_load_lds_dwordx4 v198, s[4:5]
	s_mov_b32 m0, s6
	s_addc_u32 s45, s5, 0
	s_mov_b32 s6, m0
	s_mov_b32 m0, s97
	s_nop 0
	global_load_lds_dwordx4 v199, s[58:59]
	s_mov_b32 m0, s6
	v_readlane_b32 s21, v255, 31
	s_mov_b32 s6, m0
	s_mov_b32 m0, s91
	s_nop 0
	global_load_lds_dwordx4 v200, s[58:59]
	s_mov_b32 m0, s6
	s_mov_b32 s69, 0x8000
	s_mov_b32 s6, m0
	s_mov_b32 m0, s21
	s_nop 0
	global_load_lds_dwordx4 v197, s[44:45]
	s_mov_b32 m0, s6
	s_mov_b32 s72, 0
	s_mov_b32 s6, m0
	s_mov_b32 m0, s95
	s_nop 0
	global_load_lds_dwordx4 v198, s[44:45]
	s_mov_b32 m0, s6
	s_movk_i32 s74, 0x4000
.LBB0_305:
	v_and_b32_e32 v201, 31, v195
	v_lshrrev_b32_e32 v3, 5, v196
	v_or_b32_e32 v4, s93, v201
	v_lshlrev_b32_e32 v17, 4, v3
	v_lshl_or_b32 v4, v4, 8, v17
	global_load_dwordx4 v[188:191], v4, s[2:3]
	global_load_dwordx4 v[184:187], v4, s[2:3] offset:32
	global_load_dwordx4 v[180:183], v4, s[2:3] offset:64
	global_load_dwordx4 v[176:179], v4, s[2:3] offset:96
	global_load_dwordx4 v[172:175], v4, s[2:3] offset:128
	global_load_dwordx4 v[168:171], v4, s[2:3] offset:160
	global_load_dwordx4 v[164:167], v4, s[2:3] offset:192
	global_load_dwordx4 v[160:163], v4, s[2:3] offset:224
	s_lshl_b32 s76, s7, 10
	s_add_i32 s7, s76, 0
	s_or_b32 s6, s75, s93
	s_add_i32 s7, s7, 0x18b00
	s_add_u32 s60, s4, 0x8000
	s_waitcnt vmcnt(0) lgkmcnt(0)
	s_barrier
	s_addc_u32 s61, s5, 0
	s_add_i32 s2, s69, s42
	s_mov_b32 s3, m0
	s_mov_b32 m0, s2
	s_nop 0
	global_load_lds_dwordx4 v197, s[60:61]
	s_mov_b32 m0, s3
	s_addk_i32 s2, 0x400
	s_mov_b32 s3, m0
	s_mov_b32 m0, s2
	s_nop 0
	global_load_lds_dwordx4 v198, s[60:61]
	s_mov_b32 m0, s3
	s_add_u32 s2, s58, 0x4000
	s_addc_u32 s3, s59, 0
	s_add_i32 s21, s74, s97
	s_mov_b32 s44, m0
	s_mov_b32 m0, s21
	s_nop 0
	global_load_lds_dwordx4 v199, s[2:3]
	s_mov_b32 m0, s44
	v_lshlrev_b32_e32 v202, 2, v3
	s_addk_i32 s21, 0x400
	s_mov_b32 s44, m0
	s_mov_b32 m0, s21
	s_nop 0
	global_load_lds_dwordx4 v200, s[2:3]
	s_mov_b32 m0, s44
	v_sub_u32_e32 v3, v201, v202
	v_add_u32_e32 v207, s6, v3
	v_lshlrev_b32_e32 v3, 4, v201
	s_movk_i32 s3, 0x70
	v_and_b32_e32 v4, 0x70, v3
	v_bitop3_b32 v209, v17, v3, s3 bitop3:0x78
	s_movk_i32 s3, 0x60
	s_add_i32 s2, s72, 0
	v_lshlrev_b32_e32 v208, 8, v201
	v_bitop3_b32 v210, v17, v4, 32 bitop3:0x36
	v_bitop3_b32 v211, v17, v4, 64 bitop3:0x36
	v_bitop3_b32 v212, v17, v4, s3 bitop3:0x36
	v_and_b32_e32 v250, 8, v201
	v_lshlrev_b32_e32 v250, 4, v250
	v_xor_b32_e32 v209, v209, v250
	v_xor_b32_e32 v210, v210, v250
	v_xor_b32_e32 v211, v211, v250
	v_xor_b32_e32 v212, v212, v250
	v_add3_u32 v3, s2, v209, v208
	v_add3_u32 v54, s2, v210, v208
	v_add3_u32 v62, s2, v211, v208
	v_add3_u32 v70, s2, v212, v208
	s_setprio 1
	ds_read_b128 v[4:7], v3 offset:49152
	v_xor_b32_e32 v250, 0x80, v3
	ds_read_b128 v[8:11], v250 offset:49152
	s_waitcnt vmcnt(7) lgkmcnt(1)
	v_mfma_f32_32x32x16_bf16 v[34:49], v[4:7], v[188:191], 0
	ds_read_b128 v[4:7], v3 offset:57344
	v_xor_b32_e32 v250, 0x80, v3
	ds_read_b128 v[12:15], v250 offset:57344
	s_waitcnt lgkmcnt(1)
	v_mfma_f32_32x32x16_bf16 v[18:33], v[4:7], v[188:191], 0
	ds_read_b128 v[4:7], v54 offset:49152
	v_xor_b32_e32 v250, 0x80, v54
	ds_read_b128 v[50:53], v250 offset:49152
	s_waitcnt vmcnt(6) lgkmcnt(1)
	v_mfma_f32_32x32x16_bf16 v[34:49], v[4:7], v[184:187], v[34:49]
	ds_read_b128 v[4:7], v54 offset:57344
	v_xor_b32_e32 v250, 0x80, v54
	ds_read_b128 v[54:57], v250 offset:57344
	s_waitcnt lgkmcnt(1)
	v_mfma_f32_32x32x16_bf16 v[18:33], v[4:7], v[184:187], v[18:33]
	ds_read_b128 v[4:7], v62 offset:49152
	v_xor_b32_e32 v250, 0x80, v62
	ds_read_b128 v[58:61], v250 offset:49152
	s_waitcnt vmcnt(5) lgkmcnt(1)
	v_mfma_f32_32x32x16_bf16 v[34:49], v[4:7], v[180:183], v[34:49]
	ds_read_b128 v[4:7], v62 offset:57344
	v_xor_b32_e32 v250, 0x80, v62
	ds_read_b128 v[62:65], v250 offset:57344
	s_waitcnt lgkmcnt(1)
	v_mfma_f32_32x32x16_bf16 v[18:33], v[4:7], v[180:183], v[18:33]
	ds_read_b128 v[4:7], v70 offset:49152
	v_xor_b32_e32 v250, 0x80, v70
	ds_read_b128 v[66:69], v250 offset:49152
	s_waitcnt vmcnt(4) lgkmcnt(1)
	v_mfma_f32_32x32x16_bf16 v[34:49], v[4:7], v[176:179], v[34:49]
	ds_read_b128 v[4:7], v70 offset:57344
	v_xor_b32_e32 v250, 0x80, v70
	ds_read_b128 v[70:73], v250 offset:57344
	s_waitcnt lgkmcnt(1)
	v_mfma_f32_32x32x16_bf16 v[18:33], v[4:7], v[176:179], v[18:33]
	s_waitcnt vmcnt(3)
	v_mfma_f32_32x32x16_bf16 v[34:49], v[8:11], v[172:175], v[34:49]
	v_mfma_f32_32x32x16_bf16 v[18:33], v[12:15], v[172:175], v[18:33]
	s_waitcnt vmcnt(2)
	v_mfma_f32_32x32x16_bf16 v[34:49], v[50:53], v[168:171], v[34:49]
	v_mfma_f32_32x32x16_bf16 v[18:33], v[54:57], v[168:171], v[18:33]
	s_waitcnt vmcnt(1)
	v_mfma_f32_32x32x16_bf16 v[34:49], v[58:61], v[164:167], v[34:49]
	v_mfma_f32_32x32x16_bf16 v[18:33], v[62:65], v[164:167], v[18:33]
	s_waitcnt vmcnt(0)
	v_mfma_f32_32x32x16_bf16 v[34:49], v[66:69], v[160:163], v[34:49]
	s_waitcnt lgkmcnt(0)
	v_mfma_f32_32x32x16_bf16 v[18:33], v[70:73], v[160:163], v[18:33]
	s_setprio 0
	s_cmpk_gt_u32 s6, 0x99
	s_cbranch_scc1 .LBB0_307
	v_lshlrev_b32_e32 v3, 2, v207
	v_sub_u32_e32 v3, s7, v3
	ds_read2_b32 v[4:5], v3 offset0:192 offset1:193
	ds_read2_b32 v[6:7], v3 offset0:194 offset1:195
	ds_read2_b32 v[8:9], v3 offset0:200 offset1:201
	ds_read2_b32 v[10:11], v3 offset0:202 offset1:203
	ds_read2_b32 v[12:13], v3 offset0:208 offset1:209
	ds_read2_b32 v[14:15], v3 offset0:210 offset1:211
	ds_read2_b32 v[50:51], v3 offset0:216 offset1:217
	ds_read2_b32 v[52:53], v3 offset0:218 offset1:219
	ds_read2_b32 v[54:55], v3 offset0:224 offset1:225
	ds_read2_b32 v[56:57], v3 offset0:226 offset1:227
	ds_read2_b32 v[58:59], v3 offset0:232 offset1:233
	ds_read2_b32 v[60:61], v3 offset0:234 offset1:235
	s_waitcnt lgkmcnt(4)
	v_pk_add_f32 v[48:49], v[48:49], v[52:53]
	v_pk_add_f32 v[46:47], v[46:47], v[50:51]
	v_pk_add_f32 v[44:45], v[44:45], v[14:15]
	v_pk_add_f32 v[42:43], v[42:43], v[12:13]
	ds_read2_b32 v[12:13], v3 offset0:240 offset1:241
	ds_read2_b32 v[14:15], v3 offset0:242 offset1:243
	ds_read2_b32 v[50:51], v3 offset0:248 offset1:249
	ds_read2_b32 v[52:53], v3 offset0:250 offset1:251
	v_pk_add_f32 v[40:41], v[40:41], v[10:11]
	v_pk_add_f32 v[38:39], v[38:39], v[8:9]
	v_pk_add_f32 v[36:37], v[36:37], v[6:7]
	v_pk_add_f32 v[34:35], v[34:35], v[4:5]
	s_waitcnt lgkmcnt(0)
	v_pk_add_f32 v[32:33], v[32:33], v[52:53]
	v_pk_add_f32 v[30:31], v[30:31], v[50:51]
	v_pk_add_f32 v[28:29], v[28:29], v[14:15]
	v_pk_add_f32 v[26:27], v[26:27], v[12:13]
	v_pk_add_f32 v[24:25], v[24:25], v[60:61]
	v_pk_add_f32 v[22:23], v[22:23], v[58:59]
	v_pk_add_f32 v[20:21], v[20:21], v[56:57]
	v_pk_add_f32 v[18:19], v[18:19], v[54:55]

.LBB0_309:
	s_mov_b32 s77, s74
	s_add_u32 s4, s70, 0xffffc000
	s_mov_b32 s74, s72
	s_addc_u32 s5, s71, -1
	s_add_i32 s72, s72, s42
	s_setprio 1
	s_waitcnt lgkmcnt(4)
	v_mfma_f32_32x32x16_bf16 v[112:127], v[234:237], v[188:191], 0
	ds_read_b128 v[234:237], v233 offset:57344
	v_add_f32_e32 v1, v232, v230
	v_add_f32_e32 v1, v228, v1
	v_add_f32_e32 v1, v231, v1
	v_add_f32_e32 v1, v226, v1
	s_waitcnt lgkmcnt(4)
	v_mfma_f32_32x32x16_bf16 v[96:111], v[238:241], v[188:191], 0
	ds_read_b128 v[238:241], v254 offset:49152
	v_add_f32_e32 v1, v229, v1
	v_add_f32_e32 v1, v225, v1
	v_add_f32_e32 v1, v227, v1
	v_add_f32_e32 v1, v222, v1
	v_add_f32_e32 v1, v224, v1
	s_waitcnt lgkmcnt(4)
	v_mfma_f32_32x32x16_bf16 v[112:127], v[242:245], v[184:187], v[112:127]
	ds_read_b128 v[242:245], v254 offset:57344
	s_mov_b32 s73, m0
	s_mov_b32 m0, s72
	s_nop 0
	global_load_lds_dwordx4 v197, s[4:5]
	s_mov_b32 m0, s73
	v_add_f32_e32 v1, v220, v1
	v_add_f32_e32 v1, v223, v1
	v_exp_f32_e32 v2, v128
	v_add_f32_e32 v1, v218, v1
	s_waitcnt lgkmcnt(4)
	v_mfma_f32_32x32x16_bf16 v[96:111], v[246:249], v[184:187], v[96:111]
	v_xor_b32_e32 v215, 0x80, v215
	ds_read_b128 v[246:249], v215 offset:49152
	v_exp_f32_e32 v12, v129
	v_add_f32_e32 v1, v221, v1
	v_exp_f32_e32 v13, v130
	v_add_f32_e32 v1, v217, v1
	s_waitcnt lgkmcnt(4)
	v_mfma_f32_32x32x16_bf16 v[112:127], v[250:253], v[180:183], v[112:127]
	ds_read_b128 v[250:253], v215 offset:57344
	v_exp_f32_e32 v14, v131
	v_add_f32_e32 v1, v219, v1
	v_exp_f32_e32 v15, v132
	s_waitcnt lgkmcnt(4)
	v_mfma_f32_32x32x16_bf16 v[96:111], v[234:237], v[180:183], v[96:111]
	v_xor_b32_e32 v216, 0x80, v216
	ds_read_b128 v[234:237], v216 offset:49152
	s_addk_i32 s72, 0x400
	s_mov_b32 s73, m0
	s_mov_b32 m0, s72
	s_nop 0
	global_load_lds_dwordx4 v198, s[4:5]
	s_mov_b32 m0, s73
	v_add_f32_e32 v1, v2, v1
	v_exp_f32_e32 v18, v133
	v_add_f32_e32 v1, v12, v1
	s_waitcnt lgkmcnt(4)
	v_mfma_f32_32x32x16_bf16 v[112:127], v[238:241], v[176:179], v[112:127]
	ds_read_b128 v[238:241], v216 offset:57344
	v_exp_f32_e32 v19, v134
	v_add_f32_e32 v1, v13, v1
	v_exp_f32_e32 v20, v135
	v_add_f32_e32 v1, v14, v1
	s_waitcnt lgkmcnt(4)
	v_mfma_f32_32x32x16_bf16 v[96:111], v[242:245], v[176:179], v[96:111]
	v_xor_b32_e32 v233, 0x80, v233
	ds_read_b128 v[242:245], v233 offset:49152
	v_exp_f32_e32 v21, v136
	v_add_f32_e32 v1, v15, v1
	v_exp_f32_e32 v22, v137
	s_waitcnt lgkmcnt(4)
	v_mfma_f32_32x32x16_bf16 v[112:127], v[246:249], v[172:175], v[112:127]
	ds_read_b128 v[246:249], v233 offset:57344
	s_add_i32 s4, s69, s97
	s_mov_b32 s5, m0
	s_mov_b32 m0, s4
	s_nop 0
	global_load_lds_dwordx4 v199, s[56:57]
	s_mov_b32 m0, s5
	v_add_f32_e32 v1, v18, v1
	v_exp_f32_e32 v23, v138
	v_add_f32_e32 v1, v19, v1
	v_exp_f32_e32 v24, v139
	s_waitcnt lgkmcnt(4)
	v_mfma_f32_32x32x16_bf16 v[96:111], v[250:253], v[172:175], v[96:111]
	v_xor_b32_e32 v254, 0x80, v254
	ds_read_b128 v[250:253], v254 offset:49152
	v_add_f32_e32 v1, v20, v1
	v_exp_f32_e32 v25, v140
	v_add_f32_e32 v1, v21, v1
	s_waitcnt lgkmcnt(4)
	v_mfma_f32_32x32x16_bf16 v[112:127], v[234:237], v[168:171], v[112:127]
	ds_read_b128 v[234:237], v254 offset:57344
	v_exp_f32_e32 v26, v141
	v_add_f32_e32 v1, v22, v1
	v_exp_f32_e32 v27, v142
	v_add_f32_e32 v1, v23, v1
	s_waitcnt lgkmcnt(4)
	v_mfma_f32_32x32x16_bf16 v[96:111], v[238:241], v[168:171], v[96:111]
	s_addk_i32 s4, 0x400
	s_mov_b32 s5, m0
	s_mov_b32 m0, s4
	s_nop 0
	global_load_lds_dwordx4 v200, s[56:57]
	s_mov_b32 m0, s5
	v_exp_f32_e32 v28, v143
	v_add_f32_e32 v1, v24, v1
	v_add_f32_e32 v1, v25, v1
	v_add_f32_e32 v1, v26, v1
	s_waitcnt lgkmcnt(3)
	v_mfma_f32_32x32x16_bf16 v[112:127], v[242:245], v[164:167], v[112:127]
	v_add_f32_e32 v1, v27, v1
	v_add_f32_e32 v1, v28, v1
	v_add_f32_e32 v205, v205, v1
	v_cvt_pk_bf16_f32 v4, v230, v232
	v_cvt_pk_bf16_f32 v5, v228, v231
	s_waitcnt lgkmcnt(2)
	v_mfma_f32_32x32x16_bf16 v[96:111], v[246:249], v[164:167], v[96:111]
	v_cvt_pk_bf16_f32 v6, v226, v229
	v_cvt_pk_bf16_f32 v7, v225, v227
	v_cvt_pk_bf16_f32 v8, v222, v224
	v_cvt_pk_bf16_f32 v9, v220, v223
	s_waitcnt lgkmcnt(1)
	v_mfma_f32_32x32x16_bf16 v[112:127], v[250:253], v[160:163], v[112:127]
	v_cvt_pk_bf16_f32 v10, v218, v221
	v_cvt_pk_bf16_f32 v11, v217, v219
	v_cvt_pk_bf16_f32 v12, v2, v12
	v_cvt_pk_bf16_f32 v13, v13, v14
	v_cvt_pk_bf16_f32 v14, v15, v18
	s_waitcnt lgkmcnt(0)
	v_mfma_f32_32x32x16_bf16 v[96:111], v[234:237], v[160:163], v[96:111]
	v_cvt_pk_bf16_f32 v15, v19, v20
	v_cvt_pk_bf16_f32 v18, v21, v22
	v_cvt_pk_bf16_f32 v19, v23, v24
	v_cvt_pk_bf16_f32 v20, v25, v26
	v_cvt_pk_bf16_f32 v21, v27, v28
	s_setprio 0
	v_add_u32_e32 v2, s74, v206
	ds_read_b64_tr_b16 v[22:23], v2 offset:0
	ds_read_b64_tr_b16 v[24:25], v2 offset:0x800
	ds_read_b64_tr_b16 v[26:27], v2 offset:0x1000
	ds_read_b64_tr_b16 v[28:29], v2 offset:0x1800
	ds_read_b64_tr_b16 v[128:129], v2 offset:0x2000
	ds_read_b64_tr_b16 v[130:131], v2 offset:0x2800
	ds_read_b64_tr_b16 v[132:133], v2 offset:0x3000
	ds_read_b64_tr_b16 v[134:135], v2 offset:0x3800
	s_waitcnt lgkmcnt(6)
	s_nop 0
	v_mfma_f32_32x32x16_bf16 v[32:47], v[4:7], v[22:25], v[32:47]
	ds_read_b64_tr_b16 v[22:23], v2 offset:0x200
	ds_read_b64_tr_b16 v[24:25], v2 offset:0xa00
	s_waitcnt lgkmcnt(6)
	v_mfma_f32_32x32x16_bf16 v[32:47], v[8:11], v[26:29], v[32:47]
	ds_read_b64_tr_b16 v[26:27], v2 offset:0x1200
	ds_read_b64_tr_b16 v[28:29], v2 offset:0x1a00
	s_waitcnt lgkmcnt(6)
	v_mfma_f32_32x32x16_bf16 v[32:47], v[12:15], v[128:131], v[32:47]
	ds_read_b64_tr_b16 v[128:129], v2 offset:0x2200
	ds_read_b64_tr_b16 v[130:131], v2 offset:0x2a00
	s_waitcnt lgkmcnt(6)
	v_mfma_f32_32x32x16_bf16 v[32:47], v[18:21], v[132:135], v[32:47]
	ds_read_b64_tr_b16 v[132:133], v2 offset:0x3200
	ds_read_b64_tr_b16 v[134:135], v2 offset:0x3a00
	s_waitcnt lgkmcnt(6)
	v_mfma_f32_32x32x16_bf16 v[48:63], v[4:7], v[22:25], v[48:63]
	ds_read_b64_tr_b16 v[22:23], v2 offset:0x400
	ds_read_b64_tr_b16 v[24:25], v2 offset:0xc00
	s_waitcnt lgkmcnt(6)
	v_mfma_f32_32x32x16_bf16 v[48:63], v[8:11], v[26:29], v[48:63]
	ds_read_b64_tr_b16 v[26:27], v2 offset:0x1400
	ds_read_b64_tr_b16 v[28:29], v2 offset:0x1c00
	s_waitcnt lgkmcnt(6)
	v_mfma_f32_32x32x16_bf16 v[48:63], v[12:15], v[128:131], v[48:63]
	ds_read_b64_tr_b16 v[128:129], v2 offset:0x2400
	ds_read_b64_tr_b16 v[130:131], v2 offset:0x2c00
	s_waitcnt lgkmcnt(6)
	v_mfma_f32_32x32x16_bf16 v[48:63], v[18:21], v[132:135], v[48:63]
	ds_read_b64_tr_b16 v[132:133], v2 offset:0x3400
	ds_read_b64_tr_b16 v[134:135], v2 offset:0x3c00
	s_waitcnt lgkmcnt(6)
	v_mfma_f32_32x32x16_bf16 v[64:79], v[4:7], v[22:25], v[64:79]
	ds_read_b64_tr_b16 v[22:23], v2 offset:0x600
	ds_read_b64_tr_b16 v[24:25], v2 offset:0xe00
	v_add3_u32 v215, s69, v209, v208
	s_waitcnt lgkmcnt(6)
	v_mfma_f32_32x32x16_bf16 v[64:79], v[8:11], v[26:29], v[64:79]
	ds_read_b64_tr_b16 v[26:27], v2 offset:0x1600
	ds_read_b64_tr_b16 v[28:29], v2 offset:0x1e00
	v_add3_u32 v216, s69, v210, v208
	s_waitcnt lgkmcnt(6)
	v_mfma_f32_32x32x16_bf16 v[64:79], v[12:15], v[128:131], v[64:79]
	ds_read_b64_tr_b16 v[128:129], v2 offset:0x2600
	ds_read_b64_tr_b16 v[130:131], v2 offset:0x2e00
	v_add3_u32 v233, s69, v211, v208
	s_waitcnt lgkmcnt(6)
	v_mfma_f32_32x32x16_bf16 v[64:79], v[18:21], v[132:135], v[64:79]
	ds_read_b64_tr_b16 v[132:133], v2 offset:0x3600
	ds_read_b64_tr_b16 v[134:135], v2 offset:0x3e00
	v_add3_u32 v254, s69, v212, v208
	s_waitcnt lgkmcnt(6)
	v_mfma_f32_32x32x16_bf16 v[80:95], v[4:7], v[22:25], v[80:95]
	v_max_f32_e32 v2, v113, v112
	v_max3_f32 v2, v2, v114, v115
	v_max3_f32 v2, v2, v116, v117
	v_max3_f32 v2, v2, v118, v119
	v_max3_f32 v2, v2, v120, v121
	v_max3_f32 v2, v2, v122, v123
	v_max3_f32 v2, v2, v124, v125
	v_max3_f32 v2, v2, v126, v127
	s_waitcnt lgkmcnt(4)
	v_mfma_f32_32x32x16_bf16 v[80:95], v[8:11], v[26:29], v[80:95]
	v_max3_f32 v2, v2, v96, v97
	v_max3_f32 v2, v2, v98, v99
	v_max3_f32 v2, v2, v100, v101
	v_max3_f32 v2, v2, v102, v103
	v_max3_f32 v2, v2, v104, v105
	v_max3_f32 v2, v2, v106, v107
	v_max3_f32 v2, v2, v108, v109
	v_max3_f32 v2, v2, v110, v111
	s_waitcnt lgkmcnt(2)
	v_mfma_f32_32x32x16_bf16 v[80:95], v[12:15], v[128:131], v[80:95]
	v_sub_f32_e32 v4, v2, v214
	v_cmp_ge_f32_e32 vcc, 0x42b504f3, v4
	s_waitcnt lgkmcnt(0)
	v_mfma_f32_32x32x16_bf16 v[80:95], v[18:21], v[132:135], v[80:95]
	s_cmp_eq_u64 vcc, exec
	s_cbranch_scc0 .Lattn0_slowA
.Lattn0_backA:
	s_waitcnt vmcnt(4) lgkmcnt(0)
	s_barrier
	ds_read_b128 v[234:237], v215 offset:49152
	ds_read_b128 v[238:241], v215 offset:57344
	ds_read_b128 v[242:245], v216 offset:49152
	ds_read_b128 v[246:249], v216 offset:57344
	ds_read_b128 v[250:253], v233 offset:49152
	v_mul_f32_e32 v5, 0xbe0293ee, v214
	v_fmamk_f32 v6, v112, 0x3e0293ee, v5
	v_fmamk_f32 v7, v113, 0x3e0293ee, v5
	v_fmamk_f32 v8, v114, 0x3e0293ee, v5
	v_fmamk_f32 v9, v115, 0x3e0293ee, v5
	v_fmamk_f32 v10, v116, 0x3e0293ee, v5
	v_fmamk_f32 v11, v117, 0x3e0293ee, v5
	v_fmamk_f32 v12, v118, 0x3e0293ee, v5
	v_fmamk_f32 v13, v119, 0x3e0293ee, v5
	v_fmamk_f32 v14, v120, 0x3e0293ee, v5
	v_fmamk_f32 v15, v121, 0x3e0293ee, v5
	v_fmamk_f32 v18, v122, 0x3e0293ee, v5
	v_fmamk_f32 v19, v123, 0x3e0293ee, v5
	v_fmamk_f32 v20, v124, 0x3e0293ee, v5
	v_fmamk_f32 v21, v125, 0x3e0293ee, v5
	v_fmamk_f32 v22, v126, 0x3e0293ee, v5
	v_fmamk_f32 v23, v127, 0x3e0293ee, v5
	v_fmamk_f32 v24, v96, 0x3e0293ee, v5
	v_fmamk_f32 v25, v97, 0x3e0293ee, v5
	v_fmamk_f32 v26, v98, 0x3e0293ee, v5
	v_fmamk_f32 v27, v99, 0x3e0293ee, v5
	v_fmamk_f32 v28, v100, 0x3e0293ee, v5
	v_fmamk_f32 v29, v101, 0x3e0293ee, v5
	v_fmamk_f32 v30, v102, 0x3e0293ee, v5
	v_fmamk_f32 v31, v103, 0x3e0293ee, v5
	v_fmamk_f32 v128, v104, 0x3e0293ee, v5
	v_fmamk_f32 v129, v105, 0x3e0293ee, v5
	v_fmamk_f32 v130, v106, 0x3e0293ee, v5
	v_fmamk_f32 v131, v107, 0x3e0293ee, v5
	v_fmamk_f32 v132, v108, 0x3e0293ee, v5
	v_fmamk_f32 v133, v109, 0x3e0293ee, v5
	v_fmamk_f32 v134, v110, 0x3e0293ee, v5
	v_fmac_f32_e32 v5, 0x3e0293ee, v111
	s_setprio 1
	s_waitcnt lgkmcnt(4)
	v_mfma_f32_32x32x16_bf16 v[112:127], v[234:237], v[188:191], 0
	ds_read_b128 v[234:237], v233 offset:57344
	v_exp_f32_e32 v135, v6
	v_exp_f32_e32 v136, v7
	v_exp_f32_e32 v137, v8
	v_exp_f32_e32 v138, v9
	s_waitcnt lgkmcnt(4)
	v_mfma_f32_32x32x16_bf16 v[96:111], v[238:241], v[188:191], 0
	ds_read_b128 v[238:241], v254 offset:49152
	v_exp_f32_e32 v10, v10
	v_exp_f32_e32 v11, v11
	v_exp_f32_e32 v12, v12
	s_waitcnt lgkmcnt(4)
	v_mfma_f32_32x32x16_bf16 v[112:127], v[242:245], v[184:187], v[112:127]
	ds_read_b128 v[242:245], v254 offset:57344
	s_add_i32 s4, s77, s42
	s_mov_b32 s5, m0
	s_mov_b32 m0, s4
	s_nop 0
	global_load_lds_dwordx4 v197, s[70:71]
	s_mov_b32 m0, s5
	v_exp_f32_e32 v13, v13
	v_exp_f32_e32 v14, v14
	v_exp_f32_e32 v15, v15
	v_exp_f32_e32 v18, v18
	s_waitcnt lgkmcnt(4)
	v_mfma_f32_32x32x16_bf16 v[96:111], v[246:249], v[184:187], v[96:111]
	v_xor_b32_e32 v215, 0x80, v215
	ds_read_b128 v[246:249], v215 offset:49152
	v_exp_f32_e32 v19, v19
	v_exp_f32_e32 v20, v20
	v_exp_f32_e32 v21, v21
	s_waitcnt lgkmcnt(4)
	v_mfma_f32_32x32x16_bf16 v[112:127], v[250:253], v[180:183], v[112:127]
	ds_read_b128 v[250:253], v215 offset:57344
	v_exp_f32_e32 v22, v22
	v_exp_f32_e32 v23, v23
	v_exp_f32_e32 v7, v24
	v_exp_f32_e32 v24, v25
	s_waitcnt lgkmcnt(4)
	v_mfma_f32_32x32x16_bf16 v[96:111], v[234:237], v[180:183], v[96:111]
	v_xor_b32_e32 v216, 0x80, v216
	ds_read_b128 v[234:237], v216 offset:49152
	s_addk_i32 s4, 0x400
	s_mov_b32 s5, m0
	s_mov_b32 m0, s4
	s_nop 0
	global_load_lds_dwordx4 v198, s[70:71]
	s_mov_b32 m0, s5
	v_exp_f32_e32 v25, v26
	v_exp_f32_e32 v26, v27
	v_exp_f32_e32 v27, v28
	s_waitcnt lgkmcnt(4)
	v_mfma_f32_32x32x16_bf16 v[112:127], v[238:241], v[176:179], v[112:127]
	ds_read_b128 v[238:241], v216 offset:57344
	v_exp_f32_e32 v28, v29
	v_exp_f32_e32 v29, v30
	v_exp_f32_e32 v30, v31
	v_exp_f32_e32 v31, v128
	s_waitcnt lgkmcnt(4)
	v_mfma_f32_32x32x16_bf16 v[96:111], v[242:245], v[176:179], v[96:111]
	v_xor_b32_e32 v233, 0x80, v233
	ds_read_b128 v[242:245], v233 offset:49152
	v_exp_f32_e32 v128, v129
	v_exp_f32_e32 v129, v130
	v_exp_f32_e32 v130, v131
	v_exp_f32_e32 v131, v132
	s_waitcnt lgkmcnt(4)
	v_mfma_f32_32x32x16_bf16 v[112:127], v[246:249], v[172:175], v[112:127]
	ds_read_b128 v[246:249], v233 offset:57344
	s_add_u32 s4, s56, 0x4000
	s_addc_u32 s5, s57, 0
	s_add_i32 s72, s74, s97
	s_mov_b32 s73, m0
	s_mov_b32 m0, s72
	s_nop 0
	global_load_lds_dwordx4 v199, s[4:5]
	s_mov_b32 m0, s73
	v_exp_f32_e32 v132, v133
	v_exp_f32_e32 v133, v134
	v_exp_f32_e32 v134, v5
	s_waitcnt lgkmcnt(4)
	v_mfma_f32_32x32x16_bf16 v[96:111], v[250:253], v[172:175], v[96:111]
	v_xor_b32_e32 v254, 0x80, v254
	ds_read_b128 v[250:253], v254 offset:49152
	v_add_f32_e32 v5, v136, v135
	v_add_f32_e32 v5, v137, v5
	v_add_f32_e32 v5, v138, v5
	v_add_f32_e32 v5, v10, v5
	v_add_f32_e32 v5, v11, v5
	v_add_f32_e32 v5, v12, v5
	v_add_f32_e32 v5, v13, v5
	s_waitcnt lgkmcnt(4)
	v_mfma_f32_32x32x16_bf16 v[112:127], v[234:237], v[168:171], v[112:127]
	ds_read_b128 v[234:237], v254 offset:57344
	v_add_f32_e32 v5, v14, v5
	v_add_f32_e32 v5, v15, v5
	v_add_f32_e32 v5, v18, v5
	v_add_f32_e32 v5, v19, v5
	v_add_f32_e32 v5, v20, v5
	v_add_f32_e32 v5, v21, v5
	v_add_f32_e32 v5, v22, v5
	s_waitcnt lgkmcnt(4)
	v_mfma_f32_32x32x16_bf16 v[96:111], v[238:241], v[168:171], v[96:111]
	s_addk_i32 s72, 0x400
	s_mov_b32 s73, m0
	s_mov_b32 m0, s72
	s_nop 0
	global_load_lds_dwordx4 v200, s[4:5]
	s_mov_b32 m0, s73
	v_add_f32_e32 v5, v23, v5
	v_add_f32_e32 v5, v7, v5
	v_add_f32_e32 v5, v24, v5
	v_add_f32_e32 v5, v25, v5
	v_add_f32_e32 v5, v26, v5
	v_add_f32_e32 v5, v27, v5
	v_add_f32_e32 v5, v28, v5
	s_waitcnt lgkmcnt(3)
	v_mfma_f32_32x32x16_bf16 v[112:127], v[242:245], v[164:167], v[112:127]
	v_add_f32_e32 v5, v29, v5
	v_add_f32_e32 v5, v30, v5
	v_add_f32_e32 v5, v31, v5
	v_add_f32_e32 v5, v128, v5
	v_add_f32_e32 v5, v129, v5
	v_add_f32_e32 v5, v130, v5
	v_add_f32_e32 v5, v131, v5
	s_waitcnt lgkmcnt(2)
	v_mfma_f32_32x32x16_bf16 v[96:111], v[246:249], v[164:167], v[96:111]
	v_add_f32_e32 v5, v132, v5
	v_add_f32_e32 v5, v133, v5
	v_add_f32_e32 v5, v134, v5
	v_add_f32_e32 v205, v205, v5
	v_cvt_pk_bf16_f32 v8, v135, v136
	v_cvt_pk_bf16_f32 v9, v137, v138
	v_cvt_pk_bf16_f32 v10, v10, v11
	s_waitcnt lgkmcnt(1)
	v_mfma_f32_32x32x16_bf16 v[112:127], v[250:253], v[160:163], v[112:127]
	v_cvt_pk_bf16_f32 v11, v12, v13
	v_cvt_pk_bf16_f32 v12, v14, v15
	v_cvt_pk_bf16_f32 v13, v18, v19
	v_cvt_pk_bf16_f32 v14, v20, v21
	v_cvt_pk_bf16_f32 v15, v22, v23
	v_cvt_pk_bf16_f32 v18, v7, v24
	s_waitcnt lgkmcnt(0)
	v_mfma_f32_32x32x16_bf16 v[96:111], v[234:237], v[160:163], v[96:111]
	v_cvt_pk_bf16_f32 v19, v25, v26
	v_cvt_pk_bf16_f32 v20, v27, v28
	v_cvt_pk_bf16_f32 v21, v29, v30
	v_cvt_pk_bf16_f32 v22, v31, v128
	v_cvt_pk_bf16_f32 v23, v129, v130
	v_cvt_pk_bf16_f32 v24, v131, v132
	v_cvt_pk_bf16_f32 v25, v133, v134
	s_setprio 0
	v_add_u32_e32 v7, s77, v206
	ds_read_b64_tr_b16 v[26:27], v7 offset:0
	ds_read_b64_tr_b16 v[28:29], v7 offset:0x800
	ds_read_b64_tr_b16 v[128:129], v7 offset:0x1000
	ds_read_b64_tr_b16 v[130:131], v7 offset:0x1800
	ds_read_b64_tr_b16 v[132:133], v7 offset:0x2000
	ds_read_b64_tr_b16 v[134:135], v7 offset:0x2800
	ds_read_b64_tr_b16 v[136:137], v7 offset:0x3000
	ds_read_b64_tr_b16 v[138:139], v7 offset:0x3800
	s_waitcnt lgkmcnt(6)
	s_nop 0
	v_mfma_f32_32x32x16_bf16 v[32:47], v[8:11], v[26:29], v[32:47]
	ds_read_b64_tr_b16 v[26:27], v7 offset:0x200
	ds_read_b64_tr_b16 v[28:29], v7 offset:0xa00
	s_waitcnt lgkmcnt(6)
	v_mfma_f32_32x32x16_bf16 v[32:47], v[12:15], v[128:131], v[32:47]
	ds_read_b64_tr_b16 v[128:129], v7 offset:0x1200
	ds_read_b64_tr_b16 v[130:131], v7 offset:0x1a00
	v_mul_f32_e32 v140, 0xbe0293ee, v214
	v_fmamk_f32 v230, v112, 0x3e0293ee, v140
	v_fmamk_f32 v232, v113, 0x3e0293ee, v140
	s_waitcnt lgkmcnt(6)
	v_mfma_f32_32x32x16_bf16 v[32:47], v[18:21], v[132:135], v[32:47]
	ds_read_b64_tr_b16 v[132:133], v7 offset:0x2200
	ds_read_b64_tr_b16 v[134:135], v7 offset:0x2a00
	v_exp_f32_e32 v230, v230
	v_exp_f32_e32 v232, v232
	v_fmamk_f32 v228, v114, 0x3e0293ee, v140
	v_fmamk_f32 v231, v115, 0x3e0293ee, v140
	s_waitcnt lgkmcnt(6)
	v_mfma_f32_32x32x16_bf16 v[32:47], v[22:25], v[136:139], v[32:47]
	ds_read_b64_tr_b16 v[136:137], v7 offset:0x3200
	ds_read_b64_tr_b16 v[138:139], v7 offset:0x3a00
	v_exp_f32_e32 v228, v228
	v_exp_f32_e32 v231, v231
	v_fmamk_f32 v226, v116, 0x3e0293ee, v140
	v_fmamk_f32 v229, v117, 0x3e0293ee, v140
	s_waitcnt lgkmcnt(6)
	v_mfma_f32_32x32x16_bf16 v[48:63], v[8:11], v[26:29], v[48:63]
	ds_read_b64_tr_b16 v[26:27], v7 offset:0x400
	ds_read_b64_tr_b16 v[28:29], v7 offset:0xc00
	v_exp_f32_e32 v226, v226
	v_exp_f32_e32 v229, v229
	v_fmamk_f32 v225, v118, 0x3e0293ee, v140
	v_fmamk_f32 v227, v119, 0x3e0293ee, v140
	s_waitcnt lgkmcnt(6)
	v_mfma_f32_32x32x16_bf16 v[48:63], v[12:15], v[128:131], v[48:63]
	ds_read_b64_tr_b16 v[128:129], v7 offset:0x1400
	ds_read_b64_tr_b16 v[130:131], v7 offset:0x1c00
	v_exp_f32_e32 v225, v225
	v_exp_f32_e32 v227, v227
	v_fmamk_f32 v222, v120, 0x3e0293ee, v140
	v_fmamk_f32 v224, v121, 0x3e0293ee, v140
	s_waitcnt lgkmcnt(6)
	v_mfma_f32_32x32x16_bf16 v[48:63], v[18:21], v[132:135], v[48:63]
	ds_read_b64_tr_b16 v[132:133], v7 offset:0x2400
	ds_read_b64_tr_b16 v[134:135], v7 offset:0x2c00
	v_exp_f32_e32 v222, v222
	v_exp_f32_e32 v224, v224
	v_fmamk_f32 v220, v122, 0x3e0293ee, v140
	v_fmamk_f32 v223, v123, 0x3e0293ee, v140
	s_waitcnt lgkmcnt(6)
	v_mfma_f32_32x32x16_bf16 v[48:63], v[22:25], v[136:139], v[48:63]
	ds_read_b64_tr_b16 v[136:137], v7 offset:0x3400
	ds_read_b64_tr_b16 v[138:139], v7 offset:0x3c00
	v_exp_f32_e32 v220, v220
	v_exp_f32_e32 v223, v223
	v_fmamk_f32 v218, v124, 0x3e0293ee, v140
	v_fmamk_f32 v221, v125, 0x3e0293ee, v140
	s_waitcnt lgkmcnt(6)
	v_mfma_f32_32x32x16_bf16 v[64:79], v[8:11], v[26:29], v[64:79]
	ds_read_b64_tr_b16 v[26:27], v7 offset:0x600
	ds_read_b64_tr_b16 v[28:29], v7 offset:0xe00
	v_exp_f32_e32 v218, v218
	v_exp_f32_e32 v221, v221
	v_fmamk_f32 v217, v126, 0x3e0293ee, v140
	v_fmamk_f32 v219, v127, 0x3e0293ee, v140
	s_waitcnt lgkmcnt(6)
	v_mfma_f32_32x32x16_bf16 v[64:79], v[12:15], v[128:131], v[64:79]
	ds_read_b64_tr_b16 v[128:129], v7 offset:0x1600
	ds_read_b64_tr_b16 v[130:131], v7 offset:0x1e00
	v_exp_f32_e32 v217, v217
	v_exp_f32_e32 v219, v219
	s_waitcnt lgkmcnt(6)
	v_mfma_f32_32x32x16_bf16 v[64:79], v[18:21], v[132:135], v[64:79]
	ds_read_b64_tr_b16 v[132:133], v7 offset:0x2600
	ds_read_b64_tr_b16 v[134:135], v7 offset:0x2e00
	v_add3_u32 v215, s74, v209, v208
	v_add3_u32 v216, s74, v210, v208
	s_waitcnt lgkmcnt(6)
	v_mfma_f32_32x32x16_bf16 v[64:79], v[22:25], v[136:139], v[64:79]
	ds_read_b64_tr_b16 v[136:137], v7 offset:0x3600
	ds_read_b64_tr_b16 v[138:139], v7 offset:0x3e00
	v_add3_u32 v233, s74, v211, v208
	v_add3_u32 v254, s74, v212, v208
	s_waitcnt lgkmcnt(6)
	v_mfma_f32_32x32x16_bf16 v[80:95], v[8:11], v[26:29], v[80:95]
	v_max_f32_e32 v7, v113, v112
	v_max3_f32 v7, v7, v114, v115
	v_max3_f32 v7, v7, v116, v117
	v_max3_f32 v7, v7, v118, v119
	v_max3_f32 v7, v7, v120, v121
	v_max3_f32 v7, v7, v122, v123
	v_max3_f32 v7, v7, v124, v125
	v_max3_f32 v7, v7, v126, v127
	s_waitcnt lgkmcnt(4)
	v_mfma_f32_32x32x16_bf16 v[80:95], v[12:15], v[128:131], v[80:95]
	v_max3_f32 v7, v7, v96, v97
	v_max3_f32 v7, v7, v98, v99
	v_max3_f32 v7, v7, v100, v101
	v_max3_f32 v7, v7, v102, v103
	v_max3_f32 v7, v7, v104, v105
	v_max3_f32 v7, v7, v106, v107
	v_max3_f32 v7, v7, v108, v109
	v_max3_f32 v7, v7, v110, v111
	s_waitcnt lgkmcnt(2)
	v_mfma_f32_32x32x16_bf16 v[80:95], v[18:21], v[132:135], v[80:95]
	v_sub_f32_e32 v8, v7, v214
	v_cmp_ge_f32_e32 vcc, 0x42b504f3, v8
	s_waitcnt lgkmcnt(0)
	v_mfma_f32_32x32x16_bf16 v[80:95], v[22:25], v[136:139], v[80:95]
	s_cmp_eq_u64 vcc, exec
	s_cbranch_scc0 .Lattn0_slowB

.LBB0_325:
	s_add_u32 s4, s58, 0xffffc000
	s_addc_u32 s5, s59, -1
	s_add_i32 s70, s69, s97
	s_mov_b32 s71, m0
	s_mov_b32 m0, s70
	s_nop 0
	global_load_lds_dwordx4 v199, s[4:5]
	s_mov_b32 m0, s71
	s_addk_i32 s70, 0x400
	s_mov_b32 s71, m0
	s_mov_b32 m0, s70
	s_nop 0
	global_load_lds_dwordx4 v200, s[4:5]
	s_mov_b32 m0, s71
	s_add_i32 s4, s57, 64
	s_cmp_le_i32 s4, s6
	s_cselect_b64 s[70:71], -1, 0
	s_cmp_gt_i32 s4, s6
	s_cbranch_scc1 .LBB0_327
	s_add_i32 s4, s83, 0
	v_add3_u32 v6, s4, v209, v208
	v_add3_u32 v7, s4, v210, v208
	v_add3_u32 v8, s4, v211, v208
	v_add3_u32 v9, s4, v212, v208
	s_setprio 1
	ds_read_b128 v[2:5], v6 offset:49152
	ds_read_b128 v[234:237], v6 offset:57344
	ds_read_b128 v[238:241], v7 offset:49152
	ds_read_b128 v[242:245], v7 offset:57344
	ds_read_b128 v[246:249], v8 offset:49152
	s_waitcnt lgkmcnt(4)
	v_mfma_f32_32x32x16_bf16 v[112:127], v[2:5], v[188:191], 0
	ds_read_b128 v[2:5], v8 offset:57344
	s_waitcnt lgkmcnt(4)
	v_mfma_f32_32x32x16_bf16 v[96:111], v[234:237], v[188:191], 0
	ds_read_b128 v[234:237], v9 offset:49152
	s_waitcnt lgkmcnt(4)
	v_mfma_f32_32x32x16_bf16 v[112:127], v[238:241], v[184:187], v[112:127]
	ds_read_b128 v[238:241], v9 offset:57344
	s_waitcnt lgkmcnt(4)
	v_mfma_f32_32x32x16_bf16 v[96:111], v[242:245], v[184:187], v[96:111]
	v_xor_b32_e32 v250, 0x80, v6
	ds_read_b128 v[242:245], v250 offset:49152
	s_waitcnt lgkmcnt(4)
	v_mfma_f32_32x32x16_bf16 v[112:127], v[246:249], v[180:183], v[112:127]
	v_xor_b32_e32 v250, 0x80, v6
	ds_read_b128 v[246:249], v250 offset:57344
	s_waitcnt lgkmcnt(4)
	v_mfma_f32_32x32x16_bf16 v[96:111], v[2:5], v[180:183], v[96:111]
	v_xor_b32_e32 v250, 0x80, v7
	ds_read_b128 v[2:5], v250 offset:49152
	s_waitcnt lgkmcnt(4)
	v_mfma_f32_32x32x16_bf16 v[112:127], v[234:237], v[176:179], v[112:127]
	v_xor_b32_e32 v250, 0x80, v7
	ds_read_b128 v[234:237], v250 offset:57344
	s_waitcnt lgkmcnt(4)
	v_mfma_f32_32x32x16_bf16 v[96:111], v[238:241], v[176:179], v[96:111]
	v_xor_b32_e32 v250, 0x80, v8
	ds_read_b128 v[238:241], v250 offset:49152
	s_waitcnt lgkmcnt(4)
	v_mfma_f32_32x32x16_bf16 v[112:127], v[242:245], v[172:175], v[112:127]
	v_xor_b32_e32 v250, 0x80, v8
	ds_read_b128 v[242:245], v250 offset:57344
	s_waitcnt lgkmcnt(4)
	v_mfma_f32_32x32x16_bf16 v[96:111], v[246:249], v[172:175], v[96:111]
	v_xor_b32_e32 v250, 0x80, v9
	ds_read_b128 v[246:249], v250 offset:49152
	s_waitcnt lgkmcnt(4)
	v_mfma_f32_32x32x16_bf16 v[112:127], v[2:5], v[168:171], v[112:127]
	v_xor_b32_e32 v250, 0x80, v9
	ds_read_b128 v[2:5], v250 offset:57344
	s_waitcnt lgkmcnt(4)
	v_mfma_f32_32x32x16_bf16 v[96:111], v[234:237], v[168:171], v[96:111]
	s_waitcnt lgkmcnt(3)
	v_mfma_f32_32x32x16_bf16 v[112:127], v[238:241], v[164:167], v[112:127]
	s_waitcnt lgkmcnt(2)
	v_mfma_f32_32x32x16_bf16 v[96:111], v[242:245], v[164:167], v[96:111]
	s_waitcnt lgkmcnt(1)
	v_mfma_f32_32x32x16_bf16 v[112:127], v[246:249], v[160:163], v[112:127]
	s_waitcnt lgkmcnt(0)
	v_mfma_f32_32x32x16_bf16 v[96:111], v[2:5], v[160:163], v[96:111]
	s_setprio 0
	s_branch .LBB0_328

.LBB0_341:
	s_addk_i32 s57, 0x80
	s_cmp_le_i32 s57, s6
	s_cselect_b64 s[74:75], -1, 0
	s_cmp_gt_i32 s57, s6
	s_cbranch_scc1 .LBB0_346
	s_add_i32 s76, s69, 0
	v_add3_u32 v3, s76, v209, v208
	v_add3_u32 v8, s76, v210, v208
	v_add3_u32 v9, s76, v211, v208
	v_add3_u32 v10, s76, v212, v208
	s_setprio 1
	ds_read_b128 v[4:7], v3 offset:49152
	ds_read_b128 v[234:237], v3 offset:57344
	ds_read_b128 v[238:241], v8 offset:49152
	ds_read_b128 v[242:245], v8 offset:57344
	ds_read_b128 v[246:249], v9 offset:49152
	s_waitcnt lgkmcnt(4)
	v_mfma_f32_32x32x16_bf16 v[144:159], v[4:7], v[188:191], 0
	ds_read_b128 v[4:7], v9 offset:57344
	s_waitcnt lgkmcnt(4)
	v_mfma_f32_32x32x16_bf16 v[128:143], v[234:237], v[188:191], 0
	ds_read_b128 v[234:237], v10 offset:49152
	s_waitcnt lgkmcnt(4)
	v_mfma_f32_32x32x16_bf16 v[144:159], v[238:241], v[184:187], v[144:159]
	ds_read_b128 v[238:241], v10 offset:57344
	s_waitcnt lgkmcnt(4)
	v_mfma_f32_32x32x16_bf16 v[128:143], v[242:245], v[184:187], v[128:143]
	v_xor_b32_e32 v250, 0x80, v3
	ds_read_b128 v[242:245], v250 offset:49152
	s_waitcnt lgkmcnt(4)
	v_mfma_f32_32x32x16_bf16 v[144:159], v[246:249], v[180:183], v[144:159]
	v_xor_b32_e32 v250, 0x80, v3
	ds_read_b128 v[246:249], v250 offset:57344
	s_waitcnt lgkmcnt(4)
	v_mfma_f32_32x32x16_bf16 v[128:143], v[4:7], v[180:183], v[128:143]
	v_xor_b32_e32 v250, 0x80, v8
	ds_read_b128 v[4:7], v250 offset:49152
	s_waitcnt lgkmcnt(4)
	v_mfma_f32_32x32x16_bf16 v[144:159], v[234:237], v[176:179], v[144:159]
	v_xor_b32_e32 v250, 0x80, v8
	ds_read_b128 v[234:237], v250 offset:57344
	s_waitcnt lgkmcnt(4)
	v_mfma_f32_32x32x16_bf16 v[128:143], v[238:241], v[176:179], v[128:143]
	v_xor_b32_e32 v250, 0x80, v9
	ds_read_b128 v[238:241], v250 offset:49152
	s_waitcnt lgkmcnt(4)
	v_mfma_f32_32x32x16_bf16 v[144:159], v[242:245], v[172:175], v[144:159]
	v_xor_b32_e32 v250, 0x80, v9
	ds_read_b128 v[242:245], v250 offset:57344
	s_waitcnt lgkmcnt(4)
	v_mfma_f32_32x32x16_bf16 v[128:143], v[246:249], v[172:175], v[128:143]
	v_xor_b32_e32 v250, 0x80, v10
	ds_read_b128 v[246:249], v250 offset:49152
	s_waitcnt lgkmcnt(4)
	v_mfma_f32_32x32x16_bf16 v[144:159], v[4:7], v[168:171], v[144:159]
	v_xor_b32_e32 v250, 0x80, v10
	ds_read_b128 v[4:7], v250 offset:57344
	s_waitcnt lgkmcnt(4)
	v_mfma_f32_32x32x16_bf16 v[128:143], v[234:237], v[168:171], v[128:143]
	s_waitcnt lgkmcnt(3)
	v_mfma_f32_32x32x16_bf16 v[144:159], v[238:241], v[164:167], v[144:159]
	s_waitcnt lgkmcnt(2)
	v_mfma_f32_32x32x16_bf16 v[128:143], v[242:245], v[164:167], v[128:143]
	s_waitcnt lgkmcnt(1)
	v_mfma_f32_32x32x16_bf16 v[144:159], v[246:249], v[160:163], v[144:159]
	s_waitcnt lgkmcnt(0)
	v_mfma_f32_32x32x16_bf16 v[128:143], v[4:7], v[160:163], v[128:143]
	s_setprio 0
	s_branch .LBB0_347

.LBB0_366:
	s_andn2_b64 vcc, exec, s[4:5]
	s_cbranch_vccnz .LBB0_369
	s_lshl_b32 s21, s56, 6
	s_cmp_le_i32 s21, s6
	s_cselect_b64 s[4:5], -1, 0
	s_cmp_gt_i32 s21, s6
	s_cbranch_scc1 .LBB0_370
	s_add_i32 s44, s87, 0
	v_add3_u32 v10, s44, v209, v208
	v_add3_u32 v11, s44, v210, v208
	v_add3_u32 v12, s44, v211, v208
	v_add3_u32 v13, s44, v212, v208
	s_setprio 1
	ds_read_b128 v[2:5], v10 offset:49152
	ds_read_b128 v[6:9], v10 offset:57344
	s_waitcnt lgkmcnt(1)
	v_mfma_f32_32x32x16_bf16 v[112:127], v[2:5], v[188:191], 0
	s_waitcnt lgkmcnt(0)
	v_mfma_f32_32x32x16_bf16 v[96:111], v[6:9], v[188:191], 0
	ds_read_b128 v[2:5], v11 offset:49152
	ds_read_b128 v[6:9], v11 offset:57344
	s_waitcnt lgkmcnt(1)
	v_mfma_f32_32x32x16_bf16 v[112:127], v[2:5], v[184:187], v[112:127]
	s_waitcnt lgkmcnt(0)
	v_mfma_f32_32x32x16_bf16 v[96:111], v[6:9], v[184:187], v[96:111]
	ds_read_b128 v[2:5], v12 offset:49152
	ds_read_b128 v[6:9], v12 offset:57344
	s_waitcnt lgkmcnt(1)
	v_mfma_f32_32x32x16_bf16 v[112:127], v[2:5], v[180:183], v[112:127]
	s_waitcnt lgkmcnt(0)
	v_mfma_f32_32x32x16_bf16 v[96:111], v[6:9], v[180:183], v[96:111]
	ds_read_b128 v[2:5], v13 offset:49152
	ds_read_b128 v[6:9], v13 offset:57344
	s_waitcnt lgkmcnt(1)
	v_mfma_f32_32x32x16_bf16 v[112:127], v[2:5], v[176:179], v[112:127]
	s_waitcnt lgkmcnt(0)
	v_mfma_f32_32x32x16_bf16 v[96:111], v[6:9], v[176:179], v[96:111]
	v_xor_b32_e32 v250, 0x80, v10
	ds_read_b128 v[2:5], v250 offset:49152
	v_xor_b32_e32 v250, 0x80, v10
	ds_read_b128 v[6:9], v250 offset:57344
	s_waitcnt lgkmcnt(1)
	v_mfma_f32_32x32x16_bf16 v[112:127], v[2:5], v[172:175], v[112:127]
	s_waitcnt lgkmcnt(0)
	v_mfma_f32_32x32x16_bf16 v[96:111], v[6:9], v[172:175], v[96:111]
	v_xor_b32_e32 v250, 0x80, v11
	ds_read_b128 v[2:5], v250 offset:49152
	v_xor_b32_e32 v250, 0x80, v11
	ds_read_b128 v[6:9], v250 offset:57344
	s_waitcnt lgkmcnt(1)
	v_mfma_f32_32x32x16_bf16 v[112:127], v[2:5], v[168:171], v[112:127]
	s_waitcnt lgkmcnt(0)
	v_mfma_f32_32x32x16_bf16 v[96:111], v[6:9], v[168:171], v[96:111]
	v_xor_b32_e32 v250, 0x80, v12
	ds_read_b128 v[2:5], v250 offset:49152
	v_xor_b32_e32 v250, 0x80, v12
	ds_read_b128 v[6:9], v250 offset:57344
	s_waitcnt lgkmcnt(1)
	v_mfma_f32_32x32x16_bf16 v[112:127], v[2:5], v[164:167], v[112:127]
	s_waitcnt lgkmcnt(0)
	v_mfma_f32_32x32x16_bf16 v[96:111], v[6:9], v[164:167], v[96:111]
	v_xor_b32_e32 v250, 0x80, v13
	ds_read_b128 v[2:5], v250 offset:49152
	v_xor_b32_e32 v250, 0x80, v13
	ds_read_b128 v[6:9], v250 offset:57344
	s_waitcnt lgkmcnt(1)
	v_mfma_f32_32x32x16_bf16 v[112:127], v[2:5], v[160:163], v[112:127]
	s_waitcnt lgkmcnt(0)
	v_mfma_f32_32x32x16_bf16 v[96:111], v[6:9], v[160:163], v[96:111]
	s_setprio 0
	s_branch .LBB0_371
